# scan waves run at raised priority; sample-attention forget cumsum issues its 17 per-lane loads together instead of 34 exposed round trips
# speedup vs baseline: 1.0865x; 1.0050x over previous
.LBB0_994:
	s_and_b64 vcc, exec, s[0:1]
	s_cbranch_vccz .LBB0_1002
	s_lshl_b32 s4, s26, 4
	s_lshl_b32 s5, s27, 2
	s_or_b32 s0, s5, s4
	s_waitcnt vmcnt(0)
	v_lshrrev_b32_e32 v2, 4, v100
	v_or_b32_e32 v100, s0, v2
	s_lshl_b32 s0, s24, 24
	s_add_u32 s0, s94, s0
	s_addc_u32 s1, s95, 0
	s_lshl_b32 s6, s25, 7
	s_add_u32 s0, s0, s6
	s_addc_u32 s1, s1, 0
	v_mov_b32_e32 v103, 0
	v_lshlrev_b32_e32 v102, 1, v100
	v_lshl_add_u64 v[0:1], s[0:1], 0, v[102:103]
	s_mov_b64 s[0:1], 0x6a00000
	s_add_i32 s5, s5, s4
	v_lshl_add_u64 v[104:105], v[0:1], 0, s[0:1]
	v_or_b32_e32 v0, s5, v2
	v_and_b32_e32 v110, 15, v166
	v_lshl_add_u32 v0, v0, 2, 0
	v_mov_b32_e32 v102, v103
	v_mov_b32_e32 v101, v103
	v_lshlrev_b32_e32 v111, 11, v110
	v_add_u32_e32 v112, 0x500, v0
	v_lshl_add_u32 v113, v110, 4, 0
	s_mov_b32 s6, 0
	s_movk_i32 s7, 0x7fff
	v_mov_b64_e32 v[0:1], v[102:103]
	v_mov_b64_e32 v[2:3], v[102:103]
	s_mov_b32 s4, 0x22222222
	s_mov_b32 s5, 0x22222222
	s_mov_b32 s10, 0x44444444
	s_mov_b32 s11, 0x44444444
	s_mov_b32 s12, 0x88888888
	s_mov_b32 s13, 0x88888888
	s_setprio 3
	s_barrier
.LBB0_996:
	s_bitcmp1_b32 s6, 0
	s_cselect_b32 s0, 0xc000, 0
	v_lshl_or_b32 v114, s6, 16, v111
	v_add_u32_e32 v115, s0, v112
	v_add_u32_e32 v116, s0, v113
	ds_read_b128 v[8:11], v116 offset:256
	ds_read2st64_b32 v[64:65], v115 offset1:6
	ds_read_b128 v[12:15], v116 offset:512
	ds_read_b128 v[4:7], v116
	ds_read_b128 v[16:19], v116 offset:768
	ds_read_b128 v[20:23], v116 offset:1024
	ds_read_b128 v[28:31], v116 offset:1792
	ds_read_b128 v[32:35], v116 offset:2048
	ds_read_b128 v[24:27], v116 offset:1536
	ds_read_b128 v[36:39], v116 offset:2304
	ds_read_b128 v[40:43], v116 offset:2560
	s_waitcnt lgkmcnt(5)
	v_pk_mul_f32 v[86:87], v[2:3], v[14:15]
	v_pk_fma_f32 v[86:87], v[0:1], v[12:13], v[86:87]
	v_add_f32_e32 v98, v86, v87
	v_pk_mul_f32 v[88:89], v[8:9], v[64:65] op_sel_hi:[1,0]
	v_pk_mul_f32 v[90:91], v[10:11], v[64:65] op_sel_hi:[1,0]
	v_add_f32_dpp v98, v98, v98 quad_perm:[1,0,3,2] row_mask:0xf bank_mask:0xf bound_ctrl:1
	v_pk_fma_f32 v[92:93], v[0:1], v[4:5], v[88:89]
	v_pk_fma_f32 v[94:95], v[2:3], v[6:7], v[90:91]
	v_add_f32_dpp v98, v98, v98 quad_perm:[2,3,0,1] row_mask:0xf bank_mask:0xf bound_ctrl:1
	ds_read_b128 v[48:51], v116 offset:3328
	ds_read2st64_b32 v[66:67], v115 offset0:12 offset1:18
	v_add_f32_dpp v98, v98, v98 row_half_mirror row_mask:0xf bank_mask:0xf bound_ctrl:1
	ds_read_b128 v[52:55], v116 offset:3584
	ds_read_b128 v[44:47], v116 offset:3072
	v_add_f32_dpp v98, v98, v98 row_mirror row_mask:0xf bank_mask:0xf bound_ctrl:1
	v_pk_fma_f32 v[0:1], v[16:17], v[98:99], v[92:93] op_sel_hi:[1,0,1]
	v_pk_fma_f32 v[2:3], v[18:19], v[98:99], v[94:95] op_sel_hi:[1,0,1]
	ds_read_b128 v[56:59], v116 offset:3840
	ds_read_b128 v[60:63], v116 offset:4096
	s_waitcnt lgkmcnt(6)
	v_pk_mul_f32 v[86:87], v[2:3], v[34:35]
	v_pk_mul_f32 v[96:97], v[22:23], v[2:3]
	v_pk_fma_f32 v[86:87], v[0:1], v[32:33], v[86:87]
	v_pk_fma_f32 v[96:97], v[20:21], v[0:1], v[96:97]
	v_add_f32_e32 v98, v86, v87
	v_pk_mul_f32 v[88:89], v[28:29], v[64:65] op_sel:[0,1] op_sel_hi:[1,1]
	v_pk_mul_f32 v[90:91], v[30:31], v[64:65] op_sel:[0,1] op_sel_hi:[1,1]
	v_add_f32_dpp v98, v98, v98 quad_perm:[1,0,3,2] row_mask:0xf bank_mask:0xf bound_ctrl:1
	v_pk_fma_f32 v[92:93], v[0:1], v[24:25], v[88:89]
	v_pk_fma_f32 v[94:95], v[2:3], v[26:27], v[90:91]
	v_add_f32_dpp v98, v98, v98 quad_perm:[2,3,0,1] row_mask:0xf bank_mask:0xf bound_ctrl:1
	v_add_f32_e32 v70, v96, v97
	ds_read_b128 v[8:11], v116 offset:4864
	v_add_f32_dpp v98, v98, v98 row_half_mirror row_mask:0xf bank_mask:0xf bound_ctrl:1
	ds_read_b128 v[12:15], v116 offset:5120
	ds_read_b128 v[4:7], v116 offset:4608
	v_add_f32_dpp v98, v98, v98 row_mirror row_mask:0xf bank_mask:0xf bound_ctrl:1
	v_pk_fma_f32 v[0:1], v[36:37], v[98:99], v[92:93] op_sel_hi:[1,0,1]
	v_pk_fma_f32 v[2:3], v[38:39], v[98:99], v[94:95] op_sel_hi:[1,0,1]
	ds_read_b128 v[16:19], v116 offset:5376
	ds_read_b128 v[20:23], v116 offset:5632
	s_waitcnt lgkmcnt(5)
	v_pk_mul_f32 v[86:87], v[2:3], v[54:55]
	v_pk_mul_f32 v[96:97], v[42:43], v[2:3]
	v_pk_fma_f32 v[86:87], v[0:1], v[52:53], v[86:87]
	v_pk_fma_f32 v[96:97], v[40:41], v[0:1], v[96:97]
	v_add_f32_e32 v98, v86, v87
	v_pk_mul_f32 v[88:89], v[48:49], v[66:67] op_sel_hi:[1,0]
	v_pk_mul_f32 v[90:91], v[50:51], v[66:67] op_sel_hi:[1,0]
	v_add_f32_dpp v98, v98, v98 quad_perm:[1,0,3,2] row_mask:0xf bank_mask:0xf bound_ctrl:1
	v_pk_fma_f32 v[92:93], v[0:1], v[44:45], v[88:89]
	v_pk_fma_f32 v[94:95], v[2:3], v[46:47], v[90:91]
	v_add_f32_dpp v98, v98, v98 quad_perm:[2,3,0,1] row_mask:0xf bank_mask:0xf bound_ctrl:1
	v_add_f32_e32 v71, v96, v97
	ds_read_b128 v[28:31], v116 offset:6400
	v_add_f32_dpp v98, v98, v98 row_half_mirror row_mask:0xf bank_mask:0xf bound_ctrl:1
	ds_read2st64_b32 v[64:65], v115 offset0:24 offset1:30
	ds_read_b128 v[32:35], v116 offset:6656
	v_add_f32_dpp v98, v98, v98 row_mirror row_mask:0xf bank_mask:0xf bound_ctrl:1
	v_pk_fma_f32 v[0:1], v[56:57], v[98:99], v[92:93] op_sel_hi:[1,0,1]
	v_pk_fma_f32 v[2:3], v[58:59], v[98:99], v[94:95] op_sel_hi:[1,0,1]
	ds_read_b128 v[24:27], v116 offset:6144
	ds_read_b128 v[36:39], v116 offset:6912
	ds_read_b128 v[40:43], v116 offset:7168
	s_waitcnt lgkmcnt(6)
	v_pk_mul_f32 v[86:87], v[2:3], v[14:15]
	v_pk_mul_f32 v[96:97], v[62:63], v[2:3]
	v_pk_fma_f32 v[86:87], v[0:1], v[12:13], v[86:87]
	v_pk_fma_f32 v[96:97], v[60:61], v[0:1], v[96:97]
	v_add_f32_e32 v98, v86, v87
	v_pk_mul_f32 v[88:89], v[8:9], v[66:67] op_sel:[0,1] op_sel_hi:[1,1]
	v_pk_mul_f32 v[90:91], v[10:11], v[66:67] op_sel:[0,1] op_sel_hi:[1,1]
	v_add_f32_dpp v98, v98, v98 quad_perm:[1,0,3,2] row_mask:0xf bank_mask:0xf bound_ctrl:1
	v_pk_fma_f32 v[92:93], v[0:1], v[4:5], v[88:89]
	v_pk_fma_f32 v[94:95], v[2:3], v[6:7], v[90:91]
	v_add_f32_dpp v98, v98, v98 quad_perm:[2,3,0,1] row_mask:0xf bank_mask:0xf bound_ctrl:1
	v_add_f32_e32 v72, v96, v97
	ds_read_b128 v[48:51], v116 offset:7936
	v_add_f32_dpp v98, v98, v98 row_half_mirror row_mask:0xf bank_mask:0xf bound_ctrl:1
	ds_read_b128 v[52:55], v116 offset:8192
	ds_read_b128 v[44:47], v116 offset:7680
	v_add_f32_dpp v98, v98, v98 row_mirror row_mask:0xf bank_mask:0xf bound_ctrl:1
	v_pk_fma_f32 v[0:1], v[16:17], v[98:99], v[92:93] op_sel_hi:[1,0,1]
	v_pk_fma_f32 v[2:3], v[18:19], v[98:99], v[94:95] op_sel_hi:[1,0,1]
	ds_read_b128 v[56:59], v116 offset:8448
	ds_read_b128 v[60:63], v116 offset:8704
	s_waitcnt lgkmcnt(5)
	v_pk_mul_f32 v[86:87], v[2:3], v[34:35]
	v_pk_mul_f32 v[96:97], v[22:23], v[2:3]
	v_pk_fma_f32 v[86:87], v[0:1], v[32:33], v[86:87]
	v_pk_fma_f32 v[96:97], v[20:21], v[0:1], v[96:97]
	v_add_f32_e32 v98, v86, v87
	v_pk_mul_f32 v[88:89], v[28:29], v[64:65] op_sel_hi:[1,0]
	v_pk_mul_f32 v[90:91], v[30:31], v[64:65] op_sel_hi:[1,0]
	v_add_f32_dpp v98, v98, v98 quad_perm:[1,0,3,2] row_mask:0xf bank_mask:0xf bound_ctrl:1
	v_pk_fma_f32 v[92:93], v[0:1], v[24:25], v[88:89]
	v_pk_fma_f32 v[94:95], v[2:3], v[26:27], v[90:91]
	v_add_f32_dpp v98, v98, v98 quad_perm:[2,3,0,1] row_mask:0xf bank_mask:0xf bound_ctrl:1
	v_add_f32_e32 v73, v96, v97
	ds_read_b128 v[8:11], v116 offset:9472
	v_add_f32_dpp v98, v98, v98 row_half_mirror row_mask:0xf bank_mask:0xf bound_ctrl:1
	ds_read2st64_b32 v[66:67], v115 offset0:36 offset1:42
	ds_read_b128 v[12:15], v116 offset:9728
	v_add_f32_dpp v98, v98, v98 row_mirror row_mask:0xf bank_mask:0xf bound_ctrl:1
	v_pk_fma_f32 v[0:1], v[36:37], v[98:99], v[92:93] op_sel_hi:[1,0,1]
	v_pk_fma_f32 v[2:3], v[38:39], v[98:99], v[94:95] op_sel_hi:[1,0,1]
	ds_read_b128 v[4:7], v116 offset:9216
	ds_read_b128 v[16:19], v116 offset:9984
	ds_read_b128 v[20:23], v116 offset:10240
	s_waitcnt lgkmcnt(6)
	v_pk_mul_f32 v[86:87], v[2:3], v[54:55]
	v_pk_mul_f32 v[96:97], v[42:43], v[2:3]
	v_pk_fma_f32 v[86:87], v[0:1], v[52:53], v[86:87]
	v_pk_fma_f32 v[96:97], v[40:41], v[0:1], v[96:97]
	v_add_f32_e32 v98, v86, v87
	v_pk_mul_f32 v[88:89], v[48:49], v[64:65] op_sel:[0,1] op_sel_hi:[1,1]
	v_pk_mul_f32 v[90:91], v[50:51], v[64:65] op_sel:[0,1] op_sel_hi:[1,1]
	v_add_f32_dpp v98, v98, v98 quad_perm:[1,0,3,2] row_mask:0xf bank_mask:0xf bound_ctrl:1
	v_pk_fma_f32 v[92:93], v[0:1], v[44:45], v[88:89]
	v_pk_fma_f32 v[94:95], v[2:3], v[46:47], v[90:91]
	v_add_f32_dpp v98, v98, v98 quad_perm:[2,3,0,1] row_mask:0xf bank_mask:0xf bound_ctrl:1
	v_add_f32_e32 v74, v96, v97
	ds_read_b128 v[28:31], v116 offset:11008
	v_add_f32_dpp v98, v98, v98 row_half_mirror row_mask:0xf bank_mask:0xf bound_ctrl:1
	ds_read_b128 v[32:35], v116 offset:11264
	ds_read_b128 v[24:27], v116 offset:10752
	v_add_f32_dpp v98, v98, v98 row_mirror row_mask:0xf bank_mask:0xf bound_ctrl:1
	v_pk_fma_f32 v[0:1], v[56:57], v[98:99], v[92:93] op_sel_hi:[1,0,1]
	v_pk_fma_f32 v[2:3], v[58:59], v[98:99], v[94:95] op_sel_hi:[1,0,1]
	ds_read_b128 v[36:39], v116 offset:11520
	ds_read_b128 v[40:43], v116 offset:11776
	s_waitcnt lgkmcnt(5)
	v_pk_mul_f32 v[86:87], v[2:3], v[14:15]
	v_pk_mul_f32 v[96:97], v[62:63], v[2:3]
	v_pk_fma_f32 v[86:87], v[0:1], v[12:13], v[86:87]
	v_pk_fma_f32 v[96:97], v[60:61], v[0:1], v[96:97]
	v_add_f32_e32 v98, v86, v87
	v_pk_mul_f32 v[88:89], v[8:9], v[66:67] op_sel_hi:[1,0]
	v_pk_mul_f32 v[90:91], v[10:11], v[66:67] op_sel_hi:[1,0]
	v_add_f32_dpp v98, v98, v98 quad_perm:[1,0,3,2] row_mask:0xf bank_mask:0xf bound_ctrl:1
	v_pk_fma_f32 v[92:93], v[0:1], v[4:5], v[88:89]
	v_pk_fma_f32 v[94:95], v[2:3], v[6:7], v[90:91]
	v_add_f32_dpp v98, v98, v98 quad_perm:[2,3,0,1] row_mask:0xf bank_mask:0xf bound_ctrl:1
	v_add_f32_e32 v75, v96, v97
	ds_read_b128 v[48:51], v116 offset:12544
	v_add_f32_dpp v98, v98, v98 row_half_mirror row_mask:0xf bank_mask:0xf bound_ctrl:1
	ds_read2st64_b32 v[64:65], v115 offset0:48 offset1:54
	ds_read_b128 v[52:55], v116 offset:12800
	v_add_f32_dpp v98, v98, v98 row_mirror row_mask:0xf bank_mask:0xf bound_ctrl:1
	v_pk_fma_f32 v[0:1], v[16:17], v[98:99], v[92:93] op_sel_hi:[1,0,1]
	v_pk_fma_f32 v[2:3], v[18:19], v[98:99], v[94:95] op_sel_hi:[1,0,1]
	ds_read_b128 v[44:47], v116 offset:12288
	ds_read_b128 v[56:59], v116 offset:13056
	ds_read_b128 v[60:63], v116 offset:13312
	s_waitcnt lgkmcnt(6)
	v_pk_mul_f32 v[86:87], v[2:3], v[34:35]
	v_pk_mul_f32 v[96:97], v[22:23], v[2:3]
	v_pk_fma_f32 v[86:87], v[0:1], v[32:33], v[86:87]
	v_pk_fma_f32 v[96:97], v[20:21], v[0:1], v[96:97]
	v_add_f32_e32 v98, v86, v87
	v_pk_mul_f32 v[88:89], v[28:29], v[66:67] op_sel:[0,1] op_sel_hi:[1,1]
	v_pk_mul_f32 v[90:91], v[30:31], v[66:67] op_sel:[0,1] op_sel_hi:[1,1]
	v_add_f32_dpp v98, v98, v98 quad_perm:[1,0,3,2] row_mask:0xf bank_mask:0xf bound_ctrl:1
	v_pk_fma_f32 v[92:93], v[0:1], v[24:25], v[88:89]
	v_pk_fma_f32 v[94:95], v[2:3], v[26:27], v[90:91]
	v_add_f32_dpp v98, v98, v98 quad_perm:[2,3,0,1] row_mask:0xf bank_mask:0xf bound_ctrl:1
	v_add_f32_e32 v76, v96, v97
	ds_read_b128 v[8:11], v116 offset:14080
	v_add_f32_dpp v98, v98, v98 row_half_mirror row_mask:0xf bank_mask:0xf bound_ctrl:1
	ds_read_b128 v[12:15], v116 offset:14336
	ds_read_b128 v[4:7], v116 offset:13824
	v_add_f32_dpp v98, v98, v98 row_mirror row_mask:0xf bank_mask:0xf bound_ctrl:1
	v_pk_fma_f32 v[0:1], v[36:37], v[98:99], v[92:93] op_sel_hi:[1,0,1]
	v_pk_fma_f32 v[2:3], v[38:39], v[98:99], v[94:95] op_sel_hi:[1,0,1]
	ds_read_b128 v[16:19], v116 offset:14592
	ds_read_b128 v[20:23], v116 offset:14848
	s_waitcnt lgkmcnt(5)
	v_pk_mul_f32 v[86:87], v[2:3], v[54:55]
	v_pk_mul_f32 v[96:97], v[42:43], v[2:3]
	v_pk_fma_f32 v[86:87], v[0:1], v[52:53], v[86:87]
	v_pk_fma_f32 v[96:97], v[40:41], v[0:1], v[96:97]
	v_add_f32_e32 v98, v86, v87
	v_pk_mul_f32 v[88:89], v[48:49], v[64:65] op_sel_hi:[1,0]
	v_pk_mul_f32 v[90:91], v[50:51], v[64:65] op_sel_hi:[1,0]
	v_add_f32_dpp v98, v98, v98 quad_perm:[1,0,3,2] row_mask:0xf bank_mask:0xf bound_ctrl:1
	v_pk_fma_f32 v[92:93], v[0:1], v[44:45], v[88:89]
	v_pk_fma_f32 v[94:95], v[2:3], v[46:47], v[90:91]
	v_add_f32_dpp v98, v98, v98 quad_perm:[2,3,0,1] row_mask:0xf bank_mask:0xf bound_ctrl:1
	v_add_f32_e32 v77, v96, v97
	ds_read_b128 v[28:31], v116 offset:15616
	v_add_f32_dpp v98, v98, v98 row_half_mirror row_mask:0xf bank_mask:0xf bound_ctrl:1
	ds_read2st64_b32 v[66:67], v115 offset0:60 offset1:66
	ds_read_b128 v[32:35], v116 offset:15872
	v_add_f32_dpp v98, v98, v98 row_mirror row_mask:0xf bank_mask:0xf bound_ctrl:1
	v_pk_fma_f32 v[0:1], v[56:57], v[98:99], v[92:93] op_sel_hi:[1,0,1]
	v_pk_fma_f32 v[2:3], v[58:59], v[98:99], v[94:95] op_sel_hi:[1,0,1]
	ds_read_b128 v[24:27], v116 offset:15360
	ds_read_b128 v[36:39], v116 offset:16128
	ds_read_b128 v[40:43], v116 offset:16384
	s_waitcnt lgkmcnt(6)
	v_pk_mul_f32 v[86:87], v[2:3], v[14:15]
	v_pk_mul_f32 v[96:97], v[62:63], v[2:3]
	v_pk_fma_f32 v[86:87], v[0:1], v[12:13], v[86:87]
	v_pk_fma_f32 v[96:97], v[60:61], v[0:1], v[96:97]
	v_add_f32_e32 v98, v86, v87
	v_pk_mul_f32 v[88:89], v[8:9], v[64:65] op_sel:[0,1] op_sel_hi:[1,1]
	v_pk_mul_f32 v[90:91], v[10:11], v[64:65] op_sel:[0,1] op_sel_hi:[1,1]
	v_add_f32_dpp v98, v98, v98 quad_perm:[1,0,3,2] row_mask:0xf bank_mask:0xf bound_ctrl:1
	v_pk_fma_f32 v[92:93], v[0:1], v[4:5], v[88:89]
	v_pk_fma_f32 v[94:95], v[2:3], v[6:7], v[90:91]
	v_add_f32_dpp v98, v98, v98 quad_perm:[2,3,0,1] row_mask:0xf bank_mask:0xf bound_ctrl:1
	v_add_f32_e32 v78, v96, v97
	ds_read_b128 v[48:51], v116 offset:17152
	v_add_f32_dpp v98, v98, v98 row_half_mirror row_mask:0xf bank_mask:0xf bound_ctrl:1
	ds_read_b128 v[52:55], v116 offset:17408
	ds_read_b128 v[44:47], v116 offset:16896
	v_add_f32_dpp v98, v98, v98 row_mirror row_mask:0xf bank_mask:0xf bound_ctrl:1
	v_pk_fma_f32 v[0:1], v[16:17], v[98:99], v[92:93] op_sel_hi:[1,0,1]
	v_pk_fma_f32 v[2:3], v[18:19], v[98:99], v[94:95] op_sel_hi:[1,0,1]
	ds_read_b128 v[56:59], v116 offset:17664
	ds_read_b128 v[60:63], v116 offset:17920
	s_waitcnt lgkmcnt(5)
	v_pk_mul_f32 v[86:87], v[2:3], v[34:35]
	v_pk_mul_f32 v[96:97], v[22:23], v[2:3]
	v_pk_fma_f32 v[86:87], v[0:1], v[32:33], v[86:87]
	v_pk_fma_f32 v[96:97], v[20:21], v[0:1], v[96:97]
	v_add_f32_e32 v98, v86, v87
	v_pk_mul_f32 v[88:89], v[28:29], v[66:67] op_sel_hi:[1,0]
	v_pk_mul_f32 v[90:91], v[30:31], v[66:67] op_sel_hi:[1,0]
	v_add_f32_dpp v98, v98, v98 quad_perm:[1,0,3,2] row_mask:0xf bank_mask:0xf bound_ctrl:1
	v_pk_fma_f32 v[92:93], v[0:1], v[24:25], v[88:89]
	v_pk_fma_f32 v[94:95], v[2:3], v[26:27], v[90:91]
	v_add_f32_dpp v98, v98, v98 quad_perm:[2,3,0,1] row_mask:0xf bank_mask:0xf bound_ctrl:1
	v_add_f32_e32 v79, v96, v97
	ds_read_b128 v[8:11], v116 offset:18688
	v_add_f32_dpp v98, v98, v98 row_half_mirror row_mask:0xf bank_mask:0xf bound_ctrl:1
	ds_read2st64_b32 v[64:65], v115 offset0:72 offset1:78
	ds_read_b128 v[12:15], v116 offset:18944
	v_add_f32_dpp v98, v98, v98 row_mirror row_mask:0xf bank_mask:0xf bound_ctrl:1
	v_pk_fma_f32 v[0:1], v[36:37], v[98:99], v[92:93] op_sel_hi:[1,0,1]
	v_pk_fma_f32 v[2:3], v[38:39], v[98:99], v[94:95] op_sel_hi:[1,0,1]
	ds_read_b128 v[4:7], v116 offset:18432
	ds_read_b128 v[16:19], v116 offset:19200
	ds_read_b128 v[20:23], v116 offset:19456
	s_waitcnt lgkmcnt(6)
	v_pk_mul_f32 v[86:87], v[2:3], v[54:55]
	v_pk_mul_f32 v[96:97], v[42:43], v[2:3]
	v_pk_fma_f32 v[86:87], v[0:1], v[52:53], v[86:87]
	v_pk_fma_f32 v[96:97], v[40:41], v[0:1], v[96:97]
	v_add_f32_e32 v98, v86, v87
	v_pk_mul_f32 v[88:89], v[48:49], v[66:67] op_sel:[0,1] op_sel_hi:[1,1]
	v_pk_mul_f32 v[90:91], v[50:51], v[66:67] op_sel:[0,1] op_sel_hi:[1,1]
	v_add_f32_dpp v98, v98, v98 quad_perm:[1,0,3,2] row_mask:0xf bank_mask:0xf bound_ctrl:1
	v_pk_fma_f32 v[92:93], v[0:1], v[44:45], v[88:89]
	v_pk_fma_f32 v[94:95], v[2:3], v[46:47], v[90:91]
	v_add_f32_dpp v98, v98, v98 quad_perm:[2,3,0,1] row_mask:0xf bank_mask:0xf bound_ctrl:1
	v_add_f32_e32 v80, v96, v97
	ds_read_b128 v[28:31], v116 offset:20224
	v_add_f32_dpp v98, v98, v98 row_half_mirror row_mask:0xf bank_mask:0xf bound_ctrl:1
	ds_read_b128 v[32:35], v116 offset:20480
	ds_read_b128 v[24:27], v116 offset:19968
	v_add_f32_dpp v98, v98, v98 row_mirror row_mask:0xf bank_mask:0xf bound_ctrl:1
	v_pk_fma_f32 v[0:1], v[56:57], v[98:99], v[92:93] op_sel_hi:[1,0,1]
	v_pk_fma_f32 v[2:3], v[58:59], v[98:99], v[94:95] op_sel_hi:[1,0,1]
	ds_read_b128 v[36:39], v116 offset:20736
	ds_read_b128 v[40:43], v116 offset:20992
	s_waitcnt lgkmcnt(5)
	v_pk_mul_f32 v[86:87], v[2:3], v[14:15]
	v_pk_mul_f32 v[96:97], v[62:63], v[2:3]
	v_pk_fma_f32 v[86:87], v[0:1], v[12:13], v[86:87]
	v_pk_fma_f32 v[96:97], v[60:61], v[0:1], v[96:97]
	v_add_f32_e32 v98, v86, v87
	v_pk_mul_f32 v[88:89], v[8:9], v[64:65] op_sel_hi:[1,0]
	v_pk_mul_f32 v[90:91], v[10:11], v[64:65] op_sel_hi:[1,0]
	v_add_f32_dpp v98, v98, v98 quad_perm:[1,0,3,2] row_mask:0xf bank_mask:0xf bound_ctrl:1
	v_pk_fma_f32 v[92:93], v[0:1], v[4:5], v[88:89]
	v_pk_fma_f32 v[94:95], v[2:3], v[6:7], v[90:91]
	v_add_f32_dpp v98, v98, v98 quad_perm:[2,3,0,1] row_mask:0xf bank_mask:0xf bound_ctrl:1
	v_add_f32_e32 v81, v96, v97
	ds_read_b128 v[48:51], v116 offset:21760
	v_add_f32_dpp v98, v98, v98 row_half_mirror row_mask:0xf bank_mask:0xf bound_ctrl:1
	ds_read2st64_b32 v[66:67], v115 offset0:84 offset1:90
	ds_read_b128 v[52:55], v116 offset:22016
	v_add_f32_dpp v98, v98, v98 row_mirror row_mask:0xf bank_mask:0xf bound_ctrl:1
	v_pk_fma_f32 v[0:1], v[16:17], v[98:99], v[92:93] op_sel_hi:[1,0,1]
	v_pk_fma_f32 v[2:3], v[18:19], v[98:99], v[94:95] op_sel_hi:[1,0,1]
	ds_read_b128 v[44:47], v116 offset:21504
	ds_read_b128 v[56:59], v116 offset:22272
	ds_read_b128 v[60:63], v116 offset:22528
	s_waitcnt lgkmcnt(6)
	v_pk_mul_f32 v[86:87], v[2:3], v[34:35]
	v_pk_mul_f32 v[96:97], v[22:23], v[2:3]
	v_pk_fma_f32 v[86:87], v[0:1], v[32:33], v[86:87]
	v_pk_fma_f32 v[96:97], v[20:21], v[0:1], v[96:97]
	v_add_f32_e32 v98, v86, v87
	v_pk_mul_f32 v[88:89], v[28:29], v[64:65] op_sel:[0,1] op_sel_hi:[1,1]
	v_pk_mul_f32 v[90:91], v[30:31], v[64:65] op_sel:[0,1] op_sel_hi:[1,1]
	v_add_f32_dpp v98, v98, v98 quad_perm:[1,0,3,2] row_mask:0xf bank_mask:0xf bound_ctrl:1
	v_pk_fma_f32 v[92:93], v[0:1], v[24:25], v[88:89]
	v_pk_fma_f32 v[94:95], v[2:3], v[26:27], v[90:91]
	v_add_f32_dpp v98, v98, v98 quad_perm:[2,3,0,1] row_mask:0xf bank_mask:0xf bound_ctrl:1
	v_add_f32_e32 v82, v96, v97
	ds_read_b128 v[8:11], v116 offset:23296
	v_add_f32_dpp v98, v98, v98 row_half_mirror row_mask:0xf bank_mask:0xf bound_ctrl:1
	ds_read_b128 v[12:15], v116 offset:23552
	ds_read_b128 v[4:7], v116 offset:23040
	v_add_f32_dpp v98, v98, v98 row_mirror row_mask:0xf bank_mask:0xf bound_ctrl:1
	v_pk_fma_f32 v[0:1], v[36:37], v[98:99], v[92:93] op_sel_hi:[1,0,1]
	v_pk_fma_f32 v[2:3], v[38:39], v[98:99], v[94:95] op_sel_hi:[1,0,1]
	ds_read_b128 v[16:19], v116 offset:23808
	ds_read_b128 v[20:23], v116 offset:24064
	s_waitcnt lgkmcnt(5)
	v_pk_mul_f32 v[86:87], v[2:3], v[54:55]
	v_pk_mul_f32 v[96:97], v[42:43], v[2:3]
	v_pk_fma_f32 v[86:87], v[0:1], v[52:53], v[86:87]
	v_pk_fma_f32 v[96:97], v[40:41], v[0:1], v[96:97]
	v_add_f32_e32 v98, v86, v87
	v_pk_mul_f32 v[88:89], v[48:49], v[66:67] op_sel_hi:[1,0]
	v_pk_mul_f32 v[90:91], v[50:51], v[66:67] op_sel_hi:[1,0]
	v_add_f32_dpp v98, v98, v98 quad_perm:[1,0,3,2] row_mask:0xf bank_mask:0xf bound_ctrl:1
	v_pk_fma_f32 v[92:93], v[0:1], v[44:45], v[88:89]
	v_pk_fma_f32 v[94:95], v[2:3], v[46:47], v[90:91]
	v_add_f32_dpp v98, v98, v98 quad_perm:[2,3,0,1] row_mask:0xf bank_mask:0xf bound_ctrl:1
	v_add_f32_e32 v83, v96, v97
	ds_read_b128 v[28:31], v116 offset:24832
	v_add_f32_dpp v98, v98, v98 row_half_mirror row_mask:0xf bank_mask:0xf bound_ctrl:1
	ds_read2st64_b32 v[64:65], v115 offset0:96 offset1:102
	ds_read_b128 v[32:35], v116 offset:25088
	v_add_f32_dpp v98, v98, v98 row_mirror row_mask:0xf bank_mask:0xf bound_ctrl:1
	v_pk_fma_f32 v[0:1], v[56:57], v[98:99], v[92:93] op_sel_hi:[1,0,1]
	v_pk_fma_f32 v[2:3], v[58:59], v[98:99], v[94:95] op_sel_hi:[1,0,1]
	ds_read_b128 v[24:27], v116 offset:24576
	ds_read_b128 v[36:39], v116 offset:25344
	ds_read_b128 v[40:43], v116 offset:25600
	s_waitcnt lgkmcnt(6)
	v_pk_mul_f32 v[86:87], v[2:3], v[14:15]
	v_pk_mul_f32 v[96:97], v[62:63], v[2:3]
	v_pk_fma_f32 v[86:87], v[0:1], v[12:13], v[86:87]
	v_pk_fma_f32 v[96:97], v[60:61], v[0:1], v[96:97]
	v_add_f32_e32 v98, v86, v87
	v_pk_mul_f32 v[88:89], v[8:9], v[66:67] op_sel:[0,1] op_sel_hi:[1,1]
	v_pk_mul_f32 v[90:91], v[10:11], v[66:67] op_sel:[0,1] op_sel_hi:[1,1]
	v_add_f32_dpp v98, v98, v98 quad_perm:[1,0,3,2] row_mask:0xf bank_mask:0xf bound_ctrl:1
	v_pk_fma_f32 v[92:93], v[0:1], v[4:5], v[88:89]
	v_pk_fma_f32 v[94:95], v[2:3], v[6:7], v[90:91]
	v_add_f32_dpp v98, v98, v98 quad_perm:[2,3,0,1] row_mask:0xf bank_mask:0xf bound_ctrl:1
	v_add_f32_e32 v84, v96, v97
	ds_read_b128 v[48:51], v116 offset:26368
	v_add_f32_dpp v98, v98, v98 row_half_mirror row_mask:0xf bank_mask:0xf bound_ctrl:1
	ds_read_b128 v[52:55], v116 offset:26624
	ds_read_b128 v[44:47], v116 offset:26112
	v_add_f32_dpp v98, v98, v98 row_mirror row_mask:0xf bank_mask:0xf bound_ctrl:1
	v_pk_fma_f32 v[0:1], v[16:17], v[98:99], v[92:93] op_sel_hi:[1,0,1]
	v_pk_fma_f32 v[2:3], v[18:19], v[98:99], v[94:95] op_sel_hi:[1,0,1]
	ds_read_b128 v[56:59], v116 offset:26880
	ds_read_b128 v[60:63], v116 offset:27136
	s_waitcnt lgkmcnt(5)
	v_pk_mul_f32 v[86:87], v[2:3], v[34:35]
	v_pk_mul_f32 v[96:97], v[22:23], v[2:3]
	v_pk_fma_f32 v[86:87], v[0:1], v[32:33], v[86:87]
	v_pk_fma_f32 v[96:97], v[20:21], v[0:1], v[96:97]
	v_add_f32_e32 v98, v86, v87
	v_pk_mul_f32 v[88:89], v[28:29], v[64:65] op_sel_hi:[1,0]
	v_pk_mul_f32 v[90:91], v[30:31], v[64:65] op_sel_hi:[1,0]
	v_add_f32_dpp v98, v98, v98 quad_perm:[1,0,3,2] row_mask:0xf bank_mask:0xf bound_ctrl:1
	v_pk_fma_f32 v[92:93], v[0:1], v[24:25], v[88:89]
	v_pk_fma_f32 v[94:95], v[2:3], v[26:27], v[90:91]
	v_add_f32_dpp v98, v98, v98 quad_perm:[2,3,0,1] row_mask:0xf bank_mask:0xf bound_ctrl:1
	v_add_f32_e32 v85, v96, v97
	ds_read_b128 v[8:11], v116 offset:27904
	v_add_f32_dpp v98, v98, v98 row_half_mirror row_mask:0xf bank_mask:0xf bound_ctrl:1
	ds_read2st64_b32 v[66:67], v115 offset0:108 offset1:114
	ds_read_b128 v[12:15], v116 offset:28160
	v_add_f32_dpp v98, v98, v98 row_mirror row_mask:0xf bank_mask:0xf bound_ctrl:1
	v_pk_fma_f32 v[0:1], v[36:37], v[98:99], v[92:93] op_sel_hi:[1,0,1]
	v_pk_fma_f32 v[2:3], v[38:39], v[98:99], v[94:95] op_sel_hi:[1,0,1]
	ds_read_b128 v[4:7], v116 offset:27648
	ds_read_b128 v[16:19], v116 offset:28416
	ds_read_b128 v[20:23], v116 offset:28672
	v_add_f32_dpp v70, v70, v70 row_ror:8 row_mask:0xf bank_mask:0x3 bound_ctrl:1
	v_add_f32_dpp v70, v78, v78 row_ror:8 row_mask:0xf bank_mask:0xc bound_ctrl:1
	v_add_f32_dpp v71, v71, v71 row_ror:8 row_mask:0xf bank_mask:0x3 bound_ctrl:1
	v_add_f32_dpp v71, v79, v79 row_ror:8 row_mask:0xf bank_mask:0xc bound_ctrl:1
	s_waitcnt lgkmcnt(6)
	v_pk_mul_f32 v[86:87], v[2:3], v[54:55]
	v_pk_mul_f32 v[96:97], v[42:43], v[2:3]
	v_pk_fma_f32 v[86:87], v[0:1], v[52:53], v[86:87]
	v_pk_fma_f32 v[96:97], v[40:41], v[0:1], v[96:97]
	v_add_f32_e32 v98, v86, v87
	v_pk_mul_f32 v[88:89], v[48:49], v[64:65] op_sel:[0,1] op_sel_hi:[1,1]
	v_pk_mul_f32 v[90:91], v[50:51], v[64:65] op_sel:[0,1] op_sel_hi:[1,1]
	v_add_f32_dpp v98, v98, v98 quad_perm:[1,0,3,2] row_mask:0xf bank_mask:0xf bound_ctrl:1
	v_pk_fma_f32 v[92:93], v[0:1], v[44:45], v[88:89]
	v_pk_fma_f32 v[94:95], v[2:3], v[46:47], v[90:91]
	v_add_f32_dpp v98, v98, v98 quad_perm:[2,3,0,1] row_mask:0xf bank_mask:0xf bound_ctrl:1
	v_add_f32_e32 v120, v96, v97
	ds_read_b128 v[28:31], v116 offset:29440
	v_add_f32_dpp v98, v98, v98 row_half_mirror row_mask:0xf bank_mask:0xf bound_ctrl:1
	ds_read_b128 v[32:35], v116 offset:29696
	ds_read_b128 v[24:27], v116 offset:29184
	v_add_f32_dpp v98, v98, v98 row_mirror row_mask:0xf bank_mask:0xf bound_ctrl:1
	v_pk_fma_f32 v[0:1], v[56:57], v[98:99], v[92:93] op_sel_hi:[1,0,1]
	v_pk_fma_f32 v[2:3], v[58:59], v[98:99], v[94:95] op_sel_hi:[1,0,1]
	ds_read_b128 v[36:39], v116 offset:29952
	ds_read_b128 v[40:43], v116 offset:30208
	v_add_f32_dpp v72, v72, v72 row_ror:8 row_mask:0xf bank_mask:0x3 bound_ctrl:1
	v_add_f32_dpp v72, v80, v80 row_ror:8 row_mask:0xf bank_mask:0xc bound_ctrl:1
	v_add_f32_dpp v73, v73, v73 row_ror:8 row_mask:0xf bank_mask:0x3 bound_ctrl:1
	v_add_f32_dpp v73, v81, v81 row_ror:8 row_mask:0xf bank_mask:0xc bound_ctrl:1
	s_waitcnt lgkmcnt(5)
	v_pk_mul_f32 v[86:87], v[2:3], v[14:15]
	v_pk_mul_f32 v[96:97], v[62:63], v[2:3]
	v_pk_fma_f32 v[86:87], v[0:1], v[12:13], v[86:87]
	v_pk_fma_f32 v[96:97], v[60:61], v[0:1], v[96:97]
	v_add_f32_e32 v98, v86, v87
	v_pk_mul_f32 v[88:89], v[8:9], v[66:67] op_sel_hi:[1,0]
	v_pk_mul_f32 v[90:91], v[10:11], v[66:67] op_sel_hi:[1,0]
	v_add_f32_dpp v98, v98, v98 quad_perm:[1,0,3,2] row_mask:0xf bank_mask:0xf bound_ctrl:1
	v_pk_fma_f32 v[92:93], v[0:1], v[4:5], v[88:89]
	v_pk_fma_f32 v[94:95], v[2:3], v[6:7], v[90:91]
	v_add_f32_dpp v98, v98, v98 quad_perm:[2,3,0,1] row_mask:0xf bank_mask:0xf bound_ctrl:1
	v_add_f32_e32 v121, v96, v97
	ds_read_b128 v[48:51], v116 offset:30976
	v_add_f32_dpp v98, v98, v98 row_half_mirror row_mask:0xf bank_mask:0xf bound_ctrl:1
	ds_read2st64_b32 v[64:65], v115 offset0:120 offset1:126
	ds_read_b128 v[52:55], v116 offset:31232
	v_add_f32_dpp v98, v98, v98 row_mirror row_mask:0xf bank_mask:0xf bound_ctrl:1
	v_pk_fma_f32 v[0:1], v[16:17], v[98:99], v[92:93] op_sel_hi:[1,0,1]
	v_pk_fma_f32 v[2:3], v[18:19], v[98:99], v[94:95] op_sel_hi:[1,0,1]
	ds_read_b128 v[44:47], v116 offset:30720
	ds_read_b128 v[56:59], v116 offset:31488
	ds_read_b128 v[60:63], v116 offset:31744
	v_add_f32_dpp v74, v74, v74 row_ror:8 row_mask:0xf bank_mask:0x3 bound_ctrl:1
	v_add_f32_dpp v74, v82, v82 row_ror:8 row_mask:0xf bank_mask:0xc bound_ctrl:1
	v_add_f32_dpp v75, v75, v75 row_ror:8 row_mask:0xf bank_mask:0x3 bound_ctrl:1
	v_add_f32_dpp v75, v83, v83 row_ror:8 row_mask:0xf bank_mask:0xc bound_ctrl:1
	s_waitcnt lgkmcnt(6)
	v_pk_mul_f32 v[86:87], v[2:3], v[34:35]
	v_pk_mul_f32 v[96:97], v[22:23], v[2:3]
	v_pk_fma_f32 v[86:87], v[0:1], v[32:33], v[86:87]
	v_pk_fma_f32 v[96:97], v[20:21], v[0:1], v[96:97]
	v_add_f32_e32 v98, v86, v87
	v_pk_mul_f32 v[88:89], v[28:29], v[66:67] op_sel:[0,1] op_sel_hi:[1,1]
	v_pk_mul_f32 v[90:91], v[30:31], v[66:67] op_sel:[0,1] op_sel_hi:[1,1]
	v_add_f32_dpp v98, v98, v98 quad_perm:[1,0,3,2] row_mask:0xf bank_mask:0xf bound_ctrl:1
	v_pk_fma_f32 v[92:93], v[0:1], v[24:25], v[88:89]
	v_pk_fma_f32 v[94:95], v[2:3], v[26:27], v[90:91]
	v_add_f32_dpp v98, v98, v98 quad_perm:[2,3,0,1] row_mask:0xf bank_mask:0xf bound_ctrl:1
	v_add_f32_e32 v122, v96, v97
	ds_read_b128 v[8:11], v116 offset:32512
	v_add_f32_dpp v98, v98, v98 row_half_mirror row_mask:0xf bank_mask:0xf bound_ctrl:1
	ds_read_b128 v[12:15], v116 offset:32768
	ds_read_b128 v[4:7], v116 offset:32256
	v_add_f32_dpp v98, v98, v98 row_mirror row_mask:0xf bank_mask:0xf bound_ctrl:1
	v_pk_fma_f32 v[0:1], v[36:37], v[98:99], v[92:93] op_sel_hi:[1,0,1]
	v_pk_fma_f32 v[2:3], v[38:39], v[98:99], v[94:95] op_sel_hi:[1,0,1]
	ds_read_b128 v[16:19], v116 offset:33024
	ds_read_b128 v[20:23], v116 offset:33280
	v_add_f32_dpp v76, v76, v76 row_ror:8 row_mask:0xf bank_mask:0x3 bound_ctrl:1
	v_add_f32_dpp v76, v84, v84 row_ror:8 row_mask:0xf bank_mask:0xc bound_ctrl:1
	v_add_f32_dpp v77, v77, v77 row_ror:8 row_mask:0xf bank_mask:0x3 bound_ctrl:1
	v_add_f32_dpp v77, v85, v85 row_ror:8 row_mask:0xf bank_mask:0xc bound_ctrl:1
	s_waitcnt lgkmcnt(5)
	v_pk_mul_f32 v[86:87], v[2:3], v[54:55]
	v_pk_mul_f32 v[96:97], v[42:43], v[2:3]
	v_pk_fma_f32 v[86:87], v[0:1], v[52:53], v[86:87]
	v_pk_fma_f32 v[96:97], v[40:41], v[0:1], v[96:97]
	v_add_f32_e32 v98, v86, v87
	v_pk_mul_f32 v[88:89], v[48:49], v[64:65] op_sel_hi:[1,0]
	v_pk_mul_f32 v[90:91], v[50:51], v[64:65] op_sel_hi:[1,0]
	v_add_f32_dpp v98, v98, v98 quad_perm:[1,0,3,2] row_mask:0xf bank_mask:0xf bound_ctrl:1
	v_pk_fma_f32 v[92:93], v[0:1], v[44:45], v[88:89]
	v_pk_fma_f32 v[94:95], v[2:3], v[46:47], v[90:91]
	v_add_f32_dpp v98, v98, v98 quad_perm:[2,3,0,1] row_mask:0xf bank_mask:0xf bound_ctrl:1
	v_add_f32_e32 v123, v96, v97
	ds_read_b128 v[28:31], v116 offset:34048
	v_add_f32_dpp v98, v98, v98 row_half_mirror row_mask:0xf bank_mask:0xf bound_ctrl:1
	ds_read2st64_b32 v[66:67], v115 offset0:132 offset1:138
	ds_read_b128 v[32:35], v116 offset:34304
	v_add_f32_dpp v98, v98, v98 row_mirror row_mask:0xf bank_mask:0xf bound_ctrl:1
	v_pk_fma_f32 v[0:1], v[56:57], v[98:99], v[92:93] op_sel_hi:[1,0,1]
	v_pk_fma_f32 v[2:3], v[58:59], v[98:99], v[94:95] op_sel_hi:[1,0,1]
	ds_read_b128 v[24:27], v116 offset:33792
	ds_read_b128 v[36:39], v116 offset:34560
	ds_read_b128 v[40:43], v116 offset:34816
	v_add_f32_dpp v70, v70, v70 row_shl:4 row_mask:0xf bank_mask:0x5 bound_ctrl:1
	v_add_f32_dpp v70, v74, v74 row_shr:4 row_mask:0xf bank_mask:0xa bound_ctrl:1
	v_add_f32_dpp v71, v71, v71 row_shl:4 row_mask:0xf bank_mask:0x5 bound_ctrl:1
	v_add_f32_dpp v71, v75, v75 row_shr:4 row_mask:0xf bank_mask:0xa bound_ctrl:1
	s_waitcnt lgkmcnt(6)
	v_pk_mul_f32 v[86:87], v[2:3], v[14:15]
	v_pk_mul_f32 v[96:97], v[62:63], v[2:3]
	v_pk_fma_f32 v[86:87], v[0:1], v[12:13], v[86:87]
	v_pk_fma_f32 v[96:97], v[60:61], v[0:1], v[96:97]
	v_add_f32_e32 v98, v86, v87
	v_pk_mul_f32 v[88:89], v[8:9], v[64:65] op_sel:[0,1] op_sel_hi:[1,1]
	v_pk_mul_f32 v[90:91], v[10:11], v[64:65] op_sel:[0,1] op_sel_hi:[1,1]
	v_add_f32_dpp v98, v98, v98 quad_perm:[1,0,3,2] row_mask:0xf bank_mask:0xf bound_ctrl:1
	v_pk_fma_f32 v[92:93], v[0:1], v[4:5], v[88:89]
	v_pk_fma_f32 v[94:95], v[2:3], v[6:7], v[90:91]
	v_add_f32_dpp v98, v98, v98 quad_perm:[2,3,0,1] row_mask:0xf bank_mask:0xf bound_ctrl:1
	v_add_f32_e32 v124, v96, v97
	ds_read_b128 v[48:51], v116 offset:35584
	v_add_f32_dpp v98, v98, v98 row_half_mirror row_mask:0xf bank_mask:0xf bound_ctrl:1
	ds_read_b128 v[52:55], v116 offset:35840
	ds_read_b128 v[44:47], v116 offset:35328
	v_add_f32_dpp v98, v98, v98 row_mirror row_mask:0xf bank_mask:0xf bound_ctrl:1
	v_pk_fma_f32 v[0:1], v[16:17], v[98:99], v[92:93] op_sel_hi:[1,0,1]
	v_pk_fma_f32 v[2:3], v[18:19], v[98:99], v[94:95] op_sel_hi:[1,0,1]
	ds_read_b128 v[56:59], v116 offset:36096
	ds_read_b128 v[60:63], v116 offset:36352
	v_add_f32_dpp v72, v72, v72 row_shl:4 row_mask:0xf bank_mask:0x5 bound_ctrl:1
	v_add_f32_dpp v72, v76, v76 row_shr:4 row_mask:0xf bank_mask:0xa bound_ctrl:1
	v_add_f32_dpp v73, v73, v73 row_shl:4 row_mask:0xf bank_mask:0x5 bound_ctrl:1
	v_add_f32_dpp v73, v77, v77 row_shr:4 row_mask:0xf bank_mask:0xa bound_ctrl:1
	s_waitcnt lgkmcnt(5)
	v_pk_mul_f32 v[86:87], v[2:3], v[34:35]
	v_pk_mul_f32 v[96:97], v[22:23], v[2:3]
	v_pk_fma_f32 v[86:87], v[0:1], v[32:33], v[86:87]
	v_pk_fma_f32 v[96:97], v[20:21], v[0:1], v[96:97]
	v_add_f32_e32 v98, v86, v87
	v_pk_mul_f32 v[88:89], v[28:29], v[66:67] op_sel_hi:[1,0]
	v_pk_mul_f32 v[90:91], v[30:31], v[66:67] op_sel_hi:[1,0]
	v_add_f32_dpp v98, v98, v98 quad_perm:[1,0,3,2] row_mask:0xf bank_mask:0xf bound_ctrl:1
	v_pk_fma_f32 v[92:93], v[0:1], v[24:25], v[88:89]
	v_pk_fma_f32 v[94:95], v[2:3], v[26:27], v[90:91]
	v_add_f32_dpp v98, v98, v98 quad_perm:[2,3,0,1] row_mask:0xf bank_mask:0xf bound_ctrl:1
	v_add_f32_e32 v125, v96, v97
	ds_read_b128 v[8:11], v116 offset:37120
	v_add_f32_dpp v98, v98, v98 row_half_mirror row_mask:0xf bank_mask:0xf bound_ctrl:1
	ds_read2st64_b32 v[64:65], v115 offset0:144 offset1:150
	ds_read_b128 v[12:15], v116 offset:37376
	v_add_f32_dpp v98, v98, v98 row_mirror row_mask:0xf bank_mask:0xf bound_ctrl:1
	v_pk_fma_f32 v[0:1], v[36:37], v[98:99], v[92:93] op_sel_hi:[1,0,1]
	v_pk_fma_f32 v[2:3], v[38:39], v[98:99], v[94:95] op_sel_hi:[1,0,1]
	ds_read_b128 v[4:7], v116 offset:36864
	ds_read_b128 v[16:19], v116 offset:37632
	ds_read_b128 v[20:23], v116 offset:37888
	v_add_f32_dpp v70, v70, v70 quad_perm:[1,0,3,2] row_mask:0xf bank_mask:0xf bound_ctrl:1
	v_add_f32_dpp v71, v71, v71 quad_perm:[1,0,3,2] row_mask:0xf bank_mask:0xf bound_ctrl:1
	v_add_f32_dpp v72, v72, v72 quad_perm:[1,0,3,2] row_mask:0xf bank_mask:0xf bound_ctrl:1
	v_add_f32_dpp v73, v73, v73 quad_perm:[1,0,3,2] row_mask:0xf bank_mask:0xf bound_ctrl:1
	s_waitcnt lgkmcnt(6)
	v_pk_mul_f32 v[86:87], v[2:3], v[54:55]
	v_pk_mul_f32 v[96:97], v[42:43], v[2:3]
	v_pk_fma_f32 v[86:87], v[0:1], v[52:53], v[86:87]
	v_pk_fma_f32 v[96:97], v[40:41], v[0:1], v[96:97]
	v_add_f32_e32 v98, v86, v87
	v_pk_mul_f32 v[88:89], v[48:49], v[66:67] op_sel:[0,1] op_sel_hi:[1,1]
	v_pk_mul_f32 v[90:91], v[50:51], v[66:67] op_sel:[0,1] op_sel_hi:[1,1]
	v_add_f32_dpp v98, v98, v98 quad_perm:[1,0,3,2] row_mask:0xf bank_mask:0xf bound_ctrl:1
	v_pk_fma_f32 v[92:93], v[0:1], v[44:45], v[88:89]
	v_pk_fma_f32 v[94:95], v[2:3], v[46:47], v[90:91]
	v_add_f32_dpp v98, v98, v98 quad_perm:[2,3,0,1] row_mask:0xf bank_mask:0xf bound_ctrl:1
	v_add_f32_e32 v126, v96, v97
	ds_read_b128 v[28:31], v116 offset:38656
	v_add_f32_dpp v98, v98, v98 row_half_mirror row_mask:0xf bank_mask:0xf bound_ctrl:1
	ds_read_b128 v[32:35], v116 offset:38912
	ds_read_b128 v[24:27], v116 offset:38400
	v_add_f32_dpp v98, v98, v98 row_mirror row_mask:0xf bank_mask:0xf bound_ctrl:1
	v_pk_fma_f32 v[0:1], v[56:57], v[98:99], v[92:93] op_sel_hi:[1,0,1]
	v_pk_fma_f32 v[2:3], v[58:59], v[98:99], v[94:95] op_sel_hi:[1,0,1]
	ds_read_b128 v[36:39], v116 offset:39168
	ds_read_b128 v[40:43], v116 offset:39424
	v_add_f32_dpp v70, v70, v70 quad_perm:[2,3,0,1] row_mask:0xf bank_mask:0xf bound_ctrl:1
	v_add_f32_dpp v71, v71, v71 quad_perm:[2,3,0,1] row_mask:0xf bank_mask:0xf bound_ctrl:1
	v_add_f32_dpp v72, v72, v72 quad_perm:[2,3,0,1] row_mask:0xf bank_mask:0xf bound_ctrl:1
	v_add_f32_dpp v73, v73, v73 quad_perm:[2,3,0,1] row_mask:0xf bank_mask:0xf bound_ctrl:1
	s_waitcnt lgkmcnt(5)
	v_pk_mul_f32 v[86:87], v[2:3], v[14:15]
	v_pk_mul_f32 v[96:97], v[62:63], v[2:3]
	v_pk_fma_f32 v[86:87], v[0:1], v[12:13], v[86:87]
	v_pk_fma_f32 v[96:97], v[60:61], v[0:1], v[96:97]
	v_add_f32_e32 v98, v86, v87
	v_pk_mul_f32 v[88:89], v[8:9], v[64:65] op_sel_hi:[1,0]
	v_pk_mul_f32 v[90:91], v[10:11], v[64:65] op_sel_hi:[1,0]
	v_add_f32_dpp v98, v98, v98 quad_perm:[1,0,3,2] row_mask:0xf bank_mask:0xf bound_ctrl:1
	v_pk_fma_f32 v[92:93], v[0:1], v[4:5], v[88:89]
	v_pk_fma_f32 v[94:95], v[2:3], v[6:7], v[90:91]
	v_add_f32_dpp v98, v98, v98 quad_perm:[2,3,0,1] row_mask:0xf bank_mask:0xf bound_ctrl:1
	v_add_f32_e32 v127, v96, v97
	ds_read_b128 v[48:51], v116 offset:40192
	v_add_f32_dpp v98, v98, v98 row_half_mirror row_mask:0xf bank_mask:0xf bound_ctrl:1
	ds_read2st64_b32 v[66:67], v115 offset0:156 offset1:162
	ds_read_b128 v[52:55], v116 offset:40448
	v_add_f32_dpp v98, v98, v98 row_mirror row_mask:0xf bank_mask:0xf bound_ctrl:1
	v_pk_fma_f32 v[0:1], v[16:17], v[98:99], v[92:93] op_sel_hi:[1,0,1]
	v_pk_fma_f32 v[2:3], v[18:19], v[98:99], v[94:95] op_sel_hi:[1,0,1]
	ds_read_b128 v[44:47], v116 offset:39936
	ds_read_b128 v[56:59], v116 offset:40704
	ds_read_b128 v[60:63], v116 offset:40960
	v_cndmask_b32_e64 v109, v70, v71, s[4:5]
	v_cndmask_b32_e64 v109, v109, v72, s[10:11]
	v_cndmask_b32_e64 v109, v109, v73, s[12:13]
	v_bfe_u32 v108, v109, 16, 1
	s_waitcnt lgkmcnt(6)
	v_pk_mul_f32 v[86:87], v[2:3], v[34:35]
	v_pk_mul_f32 v[96:97], v[22:23], v[2:3]
	v_pk_fma_f32 v[86:87], v[0:1], v[32:33], v[86:87]
	v_pk_fma_f32 v[96:97], v[20:21], v[0:1], v[96:97]
	v_add_f32_e32 v98, v86, v87
	v_pk_mul_f32 v[88:89], v[28:29], v[64:65] op_sel:[0,1] op_sel_hi:[1,1]
	v_pk_mul_f32 v[90:91], v[30:31], v[64:65] op_sel:[0,1] op_sel_hi:[1,1]
	v_add_f32_dpp v98, v98, v98 quad_perm:[1,0,3,2] row_mask:0xf bank_mask:0xf bound_ctrl:1
	v_pk_fma_f32 v[92:93], v[0:1], v[24:25], v[88:89]
	v_pk_fma_f32 v[94:95], v[2:3], v[26:27], v[90:91]
	v_add_f32_dpp v98, v98, v98 quad_perm:[2,3,0,1] row_mask:0xf bank_mask:0xf bound_ctrl:1
	v_add_f32_e32 v128, v96, v97
	ds_read_b128 v[8:11], v116 offset:41728
	v_add_f32_dpp v98, v98, v98 row_half_mirror row_mask:0xf bank_mask:0xf bound_ctrl:1
	ds_read_b128 v[12:15], v116 offset:41984
	ds_read_b128 v[4:7], v116 offset:41472
	v_add_f32_dpp v98, v98, v98 row_mirror row_mask:0xf bank_mask:0xf bound_ctrl:1
	v_pk_fma_f32 v[0:1], v[36:37], v[98:99], v[92:93] op_sel_hi:[1,0,1]
	v_pk_fma_f32 v[2:3], v[38:39], v[98:99], v[94:95] op_sel_hi:[1,0,1]
	ds_read_b128 v[16:19], v116 offset:42240
	ds_read_b128 v[20:23], v116 offset:42496
	v_mov_b32_e32 v102, v114
	v_add3_u32 v108, v109, v108, s7
	v_lshl_add_u64 v[106:107], v[102:103], 1, v[104:105]
	global_store_short_d16_hi v[106:107], v108, off
	s_waitcnt lgkmcnt(5)
	v_pk_mul_f32 v[86:87], v[2:3], v[54:55]
	v_pk_mul_f32 v[96:97], v[42:43], v[2:3]
	v_pk_fma_f32 v[86:87], v[0:1], v[52:53], v[86:87]
	v_pk_fma_f32 v[96:97], v[40:41], v[0:1], v[96:97]
	v_add_f32_e32 v98, v86, v87
	v_pk_mul_f32 v[88:89], v[48:49], v[66:67] op_sel_hi:[1,0]
	v_pk_mul_f32 v[90:91], v[50:51], v[66:67] op_sel_hi:[1,0]
	v_add_f32_dpp v98, v98, v98 quad_perm:[1,0,3,2] row_mask:0xf bank_mask:0xf bound_ctrl:1
	v_pk_fma_f32 v[92:93], v[0:1], v[44:45], v[88:89]
	v_pk_fma_f32 v[94:95], v[2:3], v[46:47], v[90:91]
	v_add_f32_dpp v98, v98, v98 quad_perm:[2,3,0,1] row_mask:0xf bank_mask:0xf bound_ctrl:1
	v_add_f32_e32 v129, v96, v97
	ds_read_b128 v[28:31], v116 offset:43264
	v_add_f32_dpp v98, v98, v98 row_half_mirror row_mask:0xf bank_mask:0xf bound_ctrl:1
	ds_read2st64_b32 v[64:65], v115 offset0:168 offset1:174
	ds_read_b128 v[32:35], v116 offset:43520
	v_add_f32_dpp v98, v98, v98 row_mirror row_mask:0xf bank_mask:0xf bound_ctrl:1
	v_pk_fma_f32 v[0:1], v[56:57], v[98:99], v[92:93] op_sel_hi:[1,0,1]
	v_pk_fma_f32 v[2:3], v[58:59], v[98:99], v[94:95] op_sel_hi:[1,0,1]
	ds_read_b128 v[24:27], v116 offset:43008
	ds_read_b128 v[36:39], v116 offset:43776
	ds_read_b128 v[40:43], v116 offset:44032
	s_waitcnt lgkmcnt(6)
	v_pk_mul_f32 v[86:87], v[2:3], v[14:15]
	v_pk_mul_f32 v[96:97], v[62:63], v[2:3]
	v_pk_fma_f32 v[86:87], v[0:1], v[12:13], v[86:87]
	v_pk_fma_f32 v[96:97], v[60:61], v[0:1], v[96:97]
	v_add_f32_e32 v98, v86, v87
	v_pk_mul_f32 v[88:89], v[8:9], v[66:67] op_sel:[0,1] op_sel_hi:[1,1]
	v_pk_mul_f32 v[90:91], v[10:11], v[66:67] op_sel:[0,1] op_sel_hi:[1,1]
	v_add_f32_dpp v98, v98, v98 quad_perm:[1,0,3,2] row_mask:0xf bank_mask:0xf bound_ctrl:1
	v_pk_fma_f32 v[92:93], v[0:1], v[4:5], v[88:89]
	v_pk_fma_f32 v[94:95], v[2:3], v[6:7], v[90:91]
	v_add_f32_dpp v98, v98, v98 quad_perm:[2,3,0,1] row_mask:0xf bank_mask:0xf bound_ctrl:1
	v_add_f32_e32 v130, v96, v97
	ds_read_b128 v[48:51], v116 offset:44800
	v_add_f32_dpp v98, v98, v98 row_half_mirror row_mask:0xf bank_mask:0xf bound_ctrl:1
	ds_read_b128 v[52:55], v116 offset:45056
	ds_read_b128 v[44:47], v116 offset:44544
	v_add_f32_dpp v98, v98, v98 row_mirror row_mask:0xf bank_mask:0xf bound_ctrl:1
	v_pk_fma_f32 v[0:1], v[16:17], v[98:99], v[92:93] op_sel_hi:[1,0,1]
	v_pk_fma_f32 v[2:3], v[18:19], v[98:99], v[94:95] op_sel_hi:[1,0,1]
	ds_read_b128 v[56:59], v116 offset:45312
	ds_read_b128 v[60:63], v116 offset:45568
	s_waitcnt lgkmcnt(5)
	v_pk_mul_f32 v[86:87], v[2:3], v[34:35]
	v_pk_mul_f32 v[96:97], v[22:23], v[2:3]
	v_pk_fma_f32 v[86:87], v[0:1], v[32:33], v[86:87]
	v_pk_fma_f32 v[96:97], v[20:21], v[0:1], v[96:97]
	v_add_f32_e32 v98, v86, v87
	v_pk_mul_f32 v[88:89], v[28:29], v[64:65] op_sel_hi:[1,0]
	v_pk_mul_f32 v[90:91], v[30:31], v[64:65] op_sel_hi:[1,0]
	v_add_f32_dpp v98, v98, v98 quad_perm:[1,0,3,2] row_mask:0xf bank_mask:0xf bound_ctrl:1
	v_pk_fma_f32 v[92:93], v[0:1], v[24:25], v[88:89]
	v_pk_fma_f32 v[94:95], v[2:3], v[26:27], v[90:91]
	v_add_f32_dpp v98, v98, v98 quad_perm:[2,3,0,1] row_mask:0xf bank_mask:0xf bound_ctrl:1
	v_add_f32_e32 v131, v96, v97
	ds_read_b128 v[8:11], v116 offset:46336
	v_add_f32_dpp v98, v98, v98 row_half_mirror row_mask:0xf bank_mask:0xf bound_ctrl:1
	ds_read2st64_b32 v[66:67], v115 offset0:180 offset1:186
	ds_read_b128 v[12:15], v116 offset:46592
	v_add_f32_dpp v98, v98, v98 row_mirror row_mask:0xf bank_mask:0xf bound_ctrl:1
	v_pk_fma_f32 v[0:1], v[36:37], v[98:99], v[92:93] op_sel_hi:[1,0,1]
	v_pk_fma_f32 v[2:3], v[38:39], v[98:99], v[94:95] op_sel_hi:[1,0,1]
	ds_read_b128 v[4:7], v116 offset:46080
	ds_read_b128 v[16:19], v116 offset:46848
	ds_read_b128 v[20:23], v116 offset:47104
	s_waitcnt lgkmcnt(6)
	v_pk_mul_f32 v[86:87], v[2:3], v[54:55]
	v_pk_mul_f32 v[96:97], v[42:43], v[2:3]
	v_pk_fma_f32 v[86:87], v[0:1], v[52:53], v[86:87]
	v_pk_fma_f32 v[96:97], v[40:41], v[0:1], v[96:97]
	v_add_f32_e32 v98, v86, v87
	v_pk_mul_f32 v[88:89], v[48:49], v[64:65] op_sel:[0,1] op_sel_hi:[1,1]
	v_pk_mul_f32 v[90:91], v[50:51], v[64:65] op_sel:[0,1] op_sel_hi:[1,1]
	v_add_f32_dpp v98, v98, v98 quad_perm:[1,0,3,2] row_mask:0xf bank_mask:0xf bound_ctrl:1
	v_pk_fma_f32 v[92:93], v[0:1], v[44:45], v[88:89]
	v_pk_fma_f32 v[94:95], v[2:3], v[46:47], v[90:91]
	v_add_f32_dpp v98, v98, v98 quad_perm:[2,3,0,1] row_mask:0xf bank_mask:0xf bound_ctrl:1
	v_add_f32_e32 v132, v96, v97
	ds_read_b128 v[28:31], v116 offset:47872
	v_add_f32_dpp v98, v98, v98 row_half_mirror row_mask:0xf bank_mask:0xf bound_ctrl:1
	ds_read_b128 v[32:35], v116 offset:48128
	ds_read_b128 v[24:27], v116 offset:47616
	v_add_f32_dpp v98, v98, v98 row_mirror row_mask:0xf bank_mask:0xf bound_ctrl:1
	v_pk_fma_f32 v[0:1], v[56:57], v[98:99], v[92:93] op_sel_hi:[1,0,1]
	v_pk_fma_f32 v[2:3], v[58:59], v[98:99], v[94:95] op_sel_hi:[1,0,1]
	ds_read_b128 v[36:39], v116 offset:48384
	ds_read_b128 v[40:43], v116 offset:48640
	s_waitcnt lgkmcnt(5)
	v_pk_mul_f32 v[86:87], v[2:3], v[14:15]
	v_pk_mul_f32 v[96:97], v[62:63], v[2:3]
	v_pk_fma_f32 v[86:87], v[0:1], v[12:13], v[86:87]
	v_pk_fma_f32 v[96:97], v[60:61], v[0:1], v[96:97]
	v_add_f32_e32 v98, v86, v87
	v_pk_mul_f32 v[88:89], v[8:9], v[66:67] op_sel_hi:[1,0]
	v_pk_mul_f32 v[90:91], v[10:11], v[66:67] op_sel_hi:[1,0]
	v_add_f32_dpp v98, v98, v98 quad_perm:[1,0,3,2] row_mask:0xf bank_mask:0xf bound_ctrl:1
	v_pk_fma_f32 v[92:93], v[0:1], v[4:5], v[88:89]
	v_pk_fma_f32 v[94:95], v[2:3], v[6:7], v[90:91]
	v_add_f32_dpp v98, v98, v98 quad_perm:[2,3,0,1] row_mask:0xf bank_mask:0xf bound_ctrl:1
	v_add_f32_e32 v133, v96, v97
	s_nop 0
	v_add_f32_dpp v98, v98, v98 row_half_mirror row_mask:0xf bank_mask:0xf bound_ctrl:1
	s_nop 0
	s_nop 0
	v_add_f32_dpp v98, v98, v98 row_mirror row_mask:0xf bank_mask:0xf bound_ctrl:1
	v_pk_fma_f32 v[0:1], v[16:17], v[98:99], v[92:93] op_sel_hi:[1,0,1]
	v_pk_fma_f32 v[2:3], v[18:19], v[98:99], v[94:95] op_sel_hi:[1,0,1]
	s_waitcnt lgkmcnt(0)
	v_pk_mul_f32 v[86:87], v[2:3], v[34:35]
	v_pk_mul_f32 v[96:97], v[22:23], v[2:3]
	v_pk_fma_f32 v[86:87], v[0:1], v[32:33], v[86:87]
	v_pk_fma_f32 v[96:97], v[20:21], v[0:1], v[96:97]
	v_add_f32_e32 v98, v86, v87
	v_pk_mul_f32 v[88:89], v[28:29], v[66:67] op_sel:[0,1] op_sel_hi:[1,1]
	v_pk_mul_f32 v[90:91], v[30:31], v[66:67] op_sel:[0,1] op_sel_hi:[1,1]
	v_add_f32_dpp v98, v98, v98 quad_perm:[1,0,3,2] row_mask:0xf bank_mask:0xf bound_ctrl:1
	v_pk_fma_f32 v[92:93], v[0:1], v[24:25], v[88:89]
	v_pk_fma_f32 v[94:95], v[2:3], v[26:27], v[90:91]
	v_add_f32_dpp v98, v98, v98 quad_perm:[2,3,0,1] row_mask:0xf bank_mask:0xf bound_ctrl:1
	v_add_f32_e32 v134, v96, v97
	s_nop 0
	v_add_f32_dpp v98, v98, v98 row_half_mirror row_mask:0xf bank_mask:0xf bound_ctrl:1
	s_nop 0
	s_nop 0
	v_add_f32_dpp v98, v98, v98 row_mirror row_mask:0xf bank_mask:0xf bound_ctrl:1
	v_pk_fma_f32 v[0:1], v[36:37], v[98:99], v[92:93] op_sel_hi:[1,0,1]
	v_pk_fma_f32 v[2:3], v[38:39], v[98:99], v[94:95] op_sel_hi:[1,0,1]
	v_pk_mul_f32 v[96:97], v[42:43], v[2:3]
	s_nop 0
	v_pk_fma_f32 v[96:97], v[40:41], v[0:1], v[96:97]
	v_add_f32_e32 v135, v96, v97
	s_nop 1
	v_add_f32_dpp v120, v120, v120 row_ror:8 row_mask:0xf bank_mask:0x3 bound_ctrl:1
	v_add_f32_dpp v120, v128, v128 row_ror:8 row_mask:0xf bank_mask:0xc bound_ctrl:1
	v_add_f32_dpp v121, v121, v121 row_ror:8 row_mask:0xf bank_mask:0x3 bound_ctrl:1
	v_add_f32_dpp v121, v129, v129 row_ror:8 row_mask:0xf bank_mask:0xc bound_ctrl:1
	v_add_f32_dpp v122, v122, v122 row_ror:8 row_mask:0xf bank_mask:0x3 bound_ctrl:1
	v_add_f32_dpp v122, v130, v130 row_ror:8 row_mask:0xf bank_mask:0xc bound_ctrl:1
	v_add_f32_dpp v123, v123, v123 row_ror:8 row_mask:0xf bank_mask:0x3 bound_ctrl:1
	v_add_f32_dpp v123, v131, v131 row_ror:8 row_mask:0xf bank_mask:0xc bound_ctrl:1
	v_add_f32_dpp v124, v124, v124 row_ror:8 row_mask:0xf bank_mask:0x3 bound_ctrl:1
	v_add_f32_dpp v124, v132, v132 row_ror:8 row_mask:0xf bank_mask:0xc bound_ctrl:1
	v_add_f32_dpp v125, v125, v125 row_ror:8 row_mask:0xf bank_mask:0x3 bound_ctrl:1
	v_add_f32_dpp v125, v133, v133 row_ror:8 row_mask:0xf bank_mask:0xc bound_ctrl:1
	v_add_f32_dpp v126, v126, v126 row_ror:8 row_mask:0xf bank_mask:0x3 bound_ctrl:1
	v_add_f32_dpp v126, v134, v134 row_ror:8 row_mask:0xf bank_mask:0xc bound_ctrl:1
	v_add_f32_dpp v127, v127, v127 row_ror:8 row_mask:0xf bank_mask:0x3 bound_ctrl:1
	v_add_f32_dpp v127, v135, v135 row_ror:8 row_mask:0xf bank_mask:0xc bound_ctrl:1
	v_add_f32_dpp v120, v120, v120 row_shl:4 row_mask:0xf bank_mask:0x5 bound_ctrl:1
	v_add_f32_dpp v120, v124, v124 row_shr:4 row_mask:0xf bank_mask:0xa bound_ctrl:1
	v_add_f32_dpp v121, v121, v121 row_shl:4 row_mask:0xf bank_mask:0x5 bound_ctrl:1
	v_add_f32_dpp v121, v125, v125 row_shr:4 row_mask:0xf bank_mask:0xa bound_ctrl:1
	v_add_f32_dpp v122, v122, v122 row_shl:4 row_mask:0xf bank_mask:0x5 bound_ctrl:1
	v_add_f32_dpp v122, v126, v126 row_shr:4 row_mask:0xf bank_mask:0xa bound_ctrl:1
	v_add_f32_dpp v123, v123, v123 row_shl:4 row_mask:0xf bank_mask:0x5 bound_ctrl:1
	v_add_f32_dpp v123, v127, v127 row_shr:4 row_mask:0xf bank_mask:0xa bound_ctrl:1
	v_add_f32_dpp v120, v120, v120 quad_perm:[1,0,3,2] row_mask:0xf bank_mask:0xf bound_ctrl:1
	v_add_f32_dpp v121, v121, v121 quad_perm:[1,0,3,2] row_mask:0xf bank_mask:0xf bound_ctrl:1
	v_add_f32_dpp v122, v122, v122 quad_perm:[1,0,3,2] row_mask:0xf bank_mask:0xf bound_ctrl:1
	v_add_f32_dpp v123, v123, v123 quad_perm:[1,0,3,2] row_mask:0xf bank_mask:0xf bound_ctrl:1
	v_add_f32_dpp v120, v120, v120 quad_perm:[2,3,0,1] row_mask:0xf bank_mask:0xf bound_ctrl:1
	v_add_f32_dpp v121, v121, v121 quad_perm:[2,3,0,1] row_mask:0xf bank_mask:0xf bound_ctrl:1
	v_add_f32_dpp v122, v122, v122 quad_perm:[2,3,0,1] row_mask:0xf bank_mask:0xf bound_ctrl:1
	v_add_f32_dpp v123, v123, v123 quad_perm:[2,3,0,1] row_mask:0xf bank_mask:0xf bound_ctrl:1
	v_cndmask_b32_e64 v109, v120, v121, s[4:5]
	v_cndmask_b32_e64 v109, v109, v122, s[10:11]
	v_cndmask_b32_e64 v109, v109, v123, s[12:13]
	v_bfe_u32 v108, v109, 16, 1
	v_or_b32_e32 v102, 0x8000, v114
	v_add3_u32 v108, v109, v108, s7
	v_lshl_add_u64 v[106:107], v[102:103], 1, v[104:105]
	global_store_short_d16_hi v[106:107], v108, off
	s_add_i32 s6, s6, 1
	s_cmpk_eq_i32 s6, 0x80
	s_barrier
	s_cbranch_scc0 .LBB0_996
	s_setprio 0
	s_lshl_b32 s0, s24, 16
	s_lshl_b32 s1, s25, 12
	s_or_b32 s0, s1, s0
	s_mov_b32 s1, 0
	s_lshl_b64 s[0:1], s[0:1], 2
	v_lshlrev_b64 v[4:5], 8, v[100:101]
	v_or_b32_e32 v5, s1, v5
	v_or_b32_e32 v4, s0, v4
	v_lshl_add_u64 v[4:5], s[92:93], 0, v[4:5]
	v_lshlrev_b32_e32 v6, 4, v110
	v_mov_b32_e32 v7, 0
	v_lshl_add_u64 v[4:5], v[4:5], 0, v[6:7]
	v_add_co_u32_e32 v4, vcc, 0x8180000, v4
	s_nop 1
	v_addc_co_u32_e32 v5, vcc, 0, v5, vcc
	global_store_dwordx4 v[4:5], v[0:3], off

.LBB0_1034:
	v_ashrrev_i32_e32 v5, 31, v4
	v_lshlrev_b64 v[8:9], 11, v[4:5]
	v_lshl_add_u64 v[8:9], v[2:3], 0, v[8:9]
	global_load_ushort v5, v[8:9], off
	v_add_co_u32_e32 v7, vcc, 0x200, v7
	s_xor_b64 s[10:11], vcc, -1
	s_and_b64 s[10:11], exec, s[10:11]
	v_add_u32_e32 v4, 8, v4
	s_or_b64 s[0:1], s[10:11], s[0:1]
	s_waitcnt vmcnt(0)
	v_lshlrev_b32_e32 v5, 16, v5
	ds_write_b32 v0, v5
	v_add_u32_e32 v0, 0x800, v0
	s_andn2_b64 exec, exec, s[0:1]
	s_cbranch_execnz .LBB0_1034
	s_or_b64 exec, exec, s[0:1]
	v_ashrrev_i32_e32 v120, 4, v6
	v_ashrrev_i32_e32 v121, 31, v120
	s_mov_b64 s[0:1], exec
	v_readlane_b32 s10, v238, 9
	v_readlane_b32 s11, v238, 10
	s_and_b64 s[10:11], s[0:1], s[10:11]
	s_xor_b64 s[0:1], s[10:11], s[0:1]
	s_mov_b64 exec, s[10:11]
	v_mov_b32_e32 v119, v1
	s_or_saveexec_b64 s[0:1], s[0:1]
	v_add_u32_e32 v159, 0xfffffc00, v113
	s_xor_b64 exec, exec, s[0:1]
	s_cbranch_execz .LBB0_1209
	v_readlane_b32 s44, v239, 25
	v_readlane_b32 s45, v239, 26
	v_mov_b32_e32 v119, v1
	v_lshlrev_b64 v[2:3], 16, v[120:121]
	v_lshlrev_b32_e32 v0, 2, v118
	v_add_u32_e32 v4, 0xfffffc00, v113
	v_ashrrev_i32_e32 v5, 31, v4
	v_lshlrev_b64 v[4:5], 6, v[4:5]
	v_lshl_add_u64 v[2:3], s[44:45], 0, v[2:3]
	v_lshl_add_u64 v[4:5], s[92:93], 0, v[4:5]
	v_lshl_add_u64 v[2:3], v[2:3], 0, v[0:1]
	v_lshl_add_u64 v[4:5], v[4:5], 0, v[0:1]
	v_lshl_add_u64 v[4:5], v[4:5], 0, s[8:9]
	v_mul_u32_u24_e32 v6, 17, v72
	v_mov_b32_e32 v9, 0
	v_add_u32_e32 v7, 0, v6
	v_min_u32_e32 v7, 0x40f, v7
	v_cmp_gt_u32_e32 vcc, 0x400, v7
	v_lshlrev_b32_e32 v8, 6, v7
	s_nop 0
	v_cndmask_b32_e32 v28, v4, v2, vcc
	v_cndmask_b32_e32 v29, v5, v3, vcc
	v_lshl_add_u64 v[28:29], v[28:29], 0, v[8:9]
	global_load_dword v10, v[28:29], off
	v_add_u32_e32 v7, 1, v6
	v_min_u32_e32 v7, 0x40f, v7
	v_cmp_gt_u32_e32 vcc, 0x400, v7
	v_lshlrev_b32_e32 v8, 6, v7
	s_nop 0
	v_cndmask_b32_e32 v28, v4, v2, vcc
	v_cndmask_b32_e32 v29, v5, v3, vcc
	v_lshl_add_u64 v[28:29], v[28:29], 0, v[8:9]
	global_load_dword v11, v[28:29], off
	v_add_u32_e32 v7, 2, v6
	v_min_u32_e32 v7, 0x40f, v7
	v_cmp_gt_u32_e32 vcc, 0x400, v7
	v_lshlrev_b32_e32 v8, 6, v7
	s_nop 0
	v_cndmask_b32_e32 v28, v4, v2, vcc
	v_cndmask_b32_e32 v29, v5, v3, vcc
	v_lshl_add_u64 v[28:29], v[28:29], 0, v[8:9]
	global_load_dword v12, v[28:29], off
	v_add_u32_e32 v7, 3, v6
	v_min_u32_e32 v7, 0x40f, v7
	v_cmp_gt_u32_e32 vcc, 0x400, v7
	v_lshlrev_b32_e32 v8, 6, v7
	s_nop 0
	v_cndmask_b32_e32 v28, v4, v2, vcc
	v_cndmask_b32_e32 v29, v5, v3, vcc
	v_lshl_add_u64 v[28:29], v[28:29], 0, v[8:9]
	global_load_dword v13, v[28:29], off
	v_add_u32_e32 v7, 4, v6
	v_min_u32_e32 v7, 0x40f, v7
	v_cmp_gt_u32_e32 vcc, 0x400, v7
	v_lshlrev_b32_e32 v8, 6, v7
	s_nop 0
	v_cndmask_b32_e32 v28, v4, v2, vcc
	v_cndmask_b32_e32 v29, v5, v3, vcc
	v_lshl_add_u64 v[28:29], v[28:29], 0, v[8:9]
	global_load_dword v14, v[28:29], off
	v_add_u32_e32 v7, 5, v6
	v_min_u32_e32 v7, 0x40f, v7
	v_cmp_gt_u32_e32 vcc, 0x400, v7
	v_lshlrev_b32_e32 v8, 6, v7
	s_nop 0
	v_cndmask_b32_e32 v28, v4, v2, vcc
	v_cndmask_b32_e32 v29, v5, v3, vcc
	v_lshl_add_u64 v[28:29], v[28:29], 0, v[8:9]
	global_load_dword v15, v[28:29], off
	v_add_u32_e32 v7, 6, v6
	v_min_u32_e32 v7, 0x40f, v7
	v_cmp_gt_u32_e32 vcc, 0x400, v7
	v_lshlrev_b32_e32 v8, 6, v7
	s_nop 0
	v_cndmask_b32_e32 v28, v4, v2, vcc
	v_cndmask_b32_e32 v29, v5, v3, vcc
	v_lshl_add_u64 v[28:29], v[28:29], 0, v[8:9]
	global_load_dword v16, v[28:29], off
	v_add_u32_e32 v7, 7, v6
	v_min_u32_e32 v7, 0x40f, v7
	v_cmp_gt_u32_e32 vcc, 0x400, v7
	v_lshlrev_b32_e32 v8, 6, v7
	s_nop 0
	v_cndmask_b32_e32 v28, v4, v2, vcc
	v_cndmask_b32_e32 v29, v5, v3, vcc
	v_lshl_add_u64 v[28:29], v[28:29], 0, v[8:9]
	global_load_dword v17, v[28:29], off
	v_add_u32_e32 v7, 8, v6
	v_min_u32_e32 v7, 0x40f, v7
	v_cmp_gt_u32_e32 vcc, 0x400, v7
	v_lshlrev_b32_e32 v8, 6, v7
	s_nop 0
	v_cndmask_b32_e32 v28, v4, v2, vcc
	v_cndmask_b32_e32 v29, v5, v3, vcc
	v_lshl_add_u64 v[28:29], v[28:29], 0, v[8:9]
	global_load_dword v18, v[28:29], off
	v_add_u32_e32 v7, 9, v6
	v_min_u32_e32 v7, 0x40f, v7
	v_cmp_gt_u32_e32 vcc, 0x400, v7
	v_lshlrev_b32_e32 v8, 6, v7
	s_nop 0
	v_cndmask_b32_e32 v28, v4, v2, vcc
	v_cndmask_b32_e32 v29, v5, v3, vcc
	v_lshl_add_u64 v[28:29], v[28:29], 0, v[8:9]
	global_load_dword v19, v[28:29], off
	v_add_u32_e32 v7, 10, v6
	v_min_u32_e32 v7, 0x40f, v7
	v_cmp_gt_u32_e32 vcc, 0x400, v7
	v_lshlrev_b32_e32 v8, 6, v7
	s_nop 0
	v_cndmask_b32_e32 v28, v4, v2, vcc
	v_cndmask_b32_e32 v29, v5, v3, vcc
	v_lshl_add_u64 v[28:29], v[28:29], 0, v[8:9]
	global_load_dword v20, v[28:29], off
	v_add_u32_e32 v7, 11, v6
	v_min_u32_e32 v7, 0x40f, v7
	v_cmp_gt_u32_e32 vcc, 0x400, v7
	v_lshlrev_b32_e32 v8, 6, v7
	s_nop 0
	v_cndmask_b32_e32 v28, v4, v2, vcc
	v_cndmask_b32_e32 v29, v5, v3, vcc
	v_lshl_add_u64 v[28:29], v[28:29], 0, v[8:9]
	global_load_dword v21, v[28:29], off
	v_add_u32_e32 v7, 12, v6
	v_min_u32_e32 v7, 0x40f, v7
	v_cmp_gt_u32_e32 vcc, 0x400, v7
	v_lshlrev_b32_e32 v8, 6, v7
	s_nop 0
	v_cndmask_b32_e32 v28, v4, v2, vcc
	v_cndmask_b32_e32 v29, v5, v3, vcc
	v_lshl_add_u64 v[28:29], v[28:29], 0, v[8:9]
	global_load_dword v22, v[28:29], off
	v_add_u32_e32 v7, 13, v6
	v_min_u32_e32 v7, 0x40f, v7
	v_cmp_gt_u32_e32 vcc, 0x400, v7
	v_lshlrev_b32_e32 v8, 6, v7
	s_nop 0
	v_cndmask_b32_e32 v28, v4, v2, vcc
	v_cndmask_b32_e32 v29, v5, v3, vcc
	v_lshl_add_u64 v[28:29], v[28:29], 0, v[8:9]
	global_load_dword v23, v[28:29], off
	v_add_u32_e32 v7, 14, v6
	v_min_u32_e32 v7, 0x40f, v7
	v_cmp_gt_u32_e32 vcc, 0x400, v7
	v_lshlrev_b32_e32 v8, 6, v7
	s_nop 0
	v_cndmask_b32_e32 v28, v4, v2, vcc
	v_cndmask_b32_e32 v29, v5, v3, vcc
	v_lshl_add_u64 v[28:29], v[28:29], 0, v[8:9]
	global_load_dword v24, v[28:29], off
	v_add_u32_e32 v7, 15, v6
	v_min_u32_e32 v7, 0x40f, v7
	v_cmp_gt_u32_e32 vcc, 0x400, v7
	v_lshlrev_b32_e32 v8, 6, v7
	s_nop 0
	v_cndmask_b32_e32 v28, v4, v2, vcc
	v_cndmask_b32_e32 v29, v5, v3, vcc
	v_lshl_add_u64 v[28:29], v[28:29], 0, v[8:9]
	global_load_dword v25, v[28:29], off
	v_add_u32_e32 v7, 16, v6
	v_min_u32_e32 v7, 0x40f, v7
	v_cmp_gt_u32_e32 vcc, 0x400, v7
	v_lshlrev_b32_e32 v8, 6, v7
	s_nop 0
	v_cndmask_b32_e32 v28, v4, v2, vcc
	v_cndmask_b32_e32 v29, v5, v3, vcc
	v_lshl_add_u64 v[28:29], v[28:29], 0, v[8:9]
	global_load_dword v26, v[28:29], off
	s_waitcnt vmcnt(0)
	v_cndmask_b32_e64 v10, 0, v10, s[12:13]
	v_cndmask_b32_e64 v11, 0, v11, s[12:13]
	v_cndmask_b32_e64 v12, 0, v12, s[12:13]
	v_cndmask_b32_e64 v13, 0, v13, s[16:17]
	v_cndmask_b32_e64 v14, 0, v14, s[16:17]
	v_cndmask_b32_e64 v15, 0, v15, s[16:17]
	v_cndmask_b32_e64 v16, 0, v16, s[16:17]
	v_cndmask_b32_e64 v17, 0, v17, s[16:17]
	v_cndmask_b32_e64 v18, 0, v18, s[16:17]
	v_cndmask_b32_e64 v19, 0, v19, s[16:17]
	v_cndmask_b32_e64 v20, 0, v20, s[16:17]
	v_cndmask_b32_e64 v21, 0, v21, s[16:17]
	v_cndmask_b32_e64 v22, 0, v22, s[16:17]
	v_cndmask_b32_e64 v23, 0, v23, s[16:17]
	v_cndmask_b32_e64 v24, 0, v24, s[16:17]
	v_cndmask_b32_e64 v25, 0, v25, s[16:17]
	v_cndmask_b32_e64 v26, 0, v26, s[16:17]
	v_add_f32_e32 v27, 0, v10
	v_add_f32_e32 v27, v27, v11
	v_add_f32_e32 v27, v27, v12
	v_add_f32_e32 v27, v27, v13
	v_add_f32_e32 v27, v27, v14
	v_add_f32_e32 v27, v27, v15
	v_add_f32_e32 v27, v27, v16
	v_add_f32_e32 v27, v27, v17
	v_add_f32_e32 v27, v27, v18
	v_add_f32_e32 v27, v27, v19
	v_add_f32_e32 v27, v27, v20
	v_add_f32_e32 v27, v27, v21
	v_add_f32_e32 v27, v27, v22
	v_add_f32_e32 v27, v27, v23
	v_add_f32_e32 v27, v27, v24
	v_add_f32_e32 v27, v27, v25
	v_add_f32_e32 v27, v27, v26
	v_and_b32_e32 v30, 64, v155
	v_add_u32_e32 v31, -1, v155
	v_cmp_lt_i32_e32 vcc, v31, v30
	v_add_u32_e32 v32, -2, v155
	v_readlane_b32 s10, v238, 11
	v_cndmask_b32_e32 v31, v31, v155, vcc
	v_lshlrev_b32_e32 v31, 2, v31
	ds_bpermute_b32 v31, v31, v27
	v_cmp_lt_i32_e32 vcc, v32, v30
	v_readlane_b32 s11, v238, 12
	s_waitcnt lgkmcnt(0)
	v_add_f32_e32 v31, v27, v31
	v_cndmask_b32_e32 v32, v32, v155, vcc
	v_cndmask_b32_e64 v31, v31, v27, s[10:11]
	v_lshlrev_b32_e32 v32, 2, v32
	ds_bpermute_b32 v32, v32, v31
	v_readlane_b32 s10, v238, 13
	v_readlane_b32 s11, v238, 14
	s_waitcnt lgkmcnt(0)
	v_add_f32_e32 v32, v31, v32
	v_cndmask_b32_e64 v31, v32, v31, s[10:11]
	v_add_u32_e32 v32, -4, v155
	v_cmp_lt_i32_e32 vcc, v32, v30
	v_readlane_b32 s10, v238, 15
	v_readlane_b32 s11, v238, 16
	v_cndmask_b32_e32 v32, v32, v155, vcc
	v_lshlrev_b32_e32 v32, 2, v32
	ds_bpermute_b32 v32, v32, v31
	s_waitcnt lgkmcnt(0)
	v_add_f32_e32 v32, v31, v32
	v_cndmask_b32_e64 v31, v32, v31, s[10:11]
	v_add_u32_e32 v32, -8, v155
	v_cmp_lt_i32_e32 vcc, v32, v30
	v_readlane_b32 s10, v238, 17
	v_readlane_b32 s11, v238, 18
	v_cndmask_b32_e32 v32, v32, v155, vcc
	v_lshlrev_b32_e32 v32, 2, v32
	ds_bpermute_b32 v32, v32, v31
	s_waitcnt lgkmcnt(0)
	v_add_f32_e32 v32, v31, v32
	v_cndmask_b32_e64 v31, v32, v31, s[10:11]
	v_add_u32_e32 v32, -16, v155
	v_cmp_lt_i32_e32 vcc, v32, v30
	v_readlane_b32 s10, v238, 19
	v_readlane_b32 s11, v238, 20
	v_cndmask_b32_e32 v32, v32, v155, vcc
	v_lshlrev_b32_e32 v32, 2, v32
	ds_bpermute_b32 v32, v32, v31
	s_waitcnt lgkmcnt(0)
	v_add_f32_e32 v32, v31, v32
	v_cndmask_b32_e64 v31, v32, v31, s[10:11]
	v_subrev_u32_e32 v32, 32, v155
	v_cmp_lt_i32_e32 vcc, v32, v30
	v_readlane_b32 s10, v238, 21
	v_readlane_b32 s11, v238, 22
	v_cndmask_b32_e32 v30, v32, v155, vcc
	v_lshlrev_b32_e32 v30, 2, v30
	ds_bpermute_b32 v30, v30, v31
	s_waitcnt lgkmcnt(0)
	v_add_f32_e32 v30, v31, v30
	v_cndmask_b32_e64 v30, v30, v31, s[10:11]
	v_sub_f32_e32 v27, v30, v27
	s_mov_b64 s[22:23], exec
	s_and_b64 exec, s[22:23], s[12:13]
	v_add_f32_e32 v27, v27, v10
	v_mul_f32_e32 v30, 0xbfb8aa3b, v27
	ds_write_b32 v131, v30 offset:4096
	v_add_f32_e32 v27, v27, v11
	v_mul_f32_e32 v30, 0xbfb8aa3b, v27
	ds_write_b32 v131, v30 offset:4100
	v_add_f32_e32 v27, v27, v12
	v_mul_f32_e32 v30, 0xbfb8aa3b, v27
	ds_write_b32 v131, v30 offset:4104
	s_and_b64 exec, s[22:23], s[16:17]
	v_add_f32_e32 v27, v27, v13
	v_mul_f32_e32 v30, 0xbfb8aa3b, v27
	ds_write_b32 v131, v30 offset:4108
	v_add_f32_e32 v27, v27, v14
	v_mul_f32_e32 v30, 0xbfb8aa3b, v27
	ds_write_b32 v131, v30 offset:4112
	v_add_f32_e32 v27, v27, v15
	v_mul_f32_e32 v30, 0xbfb8aa3b, v27
	ds_write_b32 v131, v30 offset:4116
	v_add_f32_e32 v27, v27, v16
	v_mul_f32_e32 v30, 0xbfb8aa3b, v27
	ds_write_b32 v131, v30 offset:4120
	v_add_f32_e32 v27, v27, v17
	v_mul_f32_e32 v30, 0xbfb8aa3b, v27
	ds_write_b32 v131, v30 offset:4124
	v_add_f32_e32 v27, v27, v18
	v_mul_f32_e32 v30, 0xbfb8aa3b, v27
	ds_write_b32 v131, v30 offset:4128
	v_add_f32_e32 v27, v27, v19
	v_mul_f32_e32 v30, 0xbfb8aa3b, v27
	ds_write_b32 v131, v30 offset:4132
	v_add_f32_e32 v27, v27, v20
	v_mul_f32_e32 v30, 0xbfb8aa3b, v27
	ds_write_b32 v131, v30 offset:4136
	v_add_f32_e32 v27, v27, v21
	v_mul_f32_e32 v30, 0xbfb8aa3b, v27
	ds_write_b32 v131, v30 offset:4140
	v_add_f32_e32 v27, v27, v22
	v_mul_f32_e32 v30, 0xbfb8aa3b, v27
	ds_write_b32 v131, v30 offset:4144
	v_add_f32_e32 v27, v27, v23
	v_mul_f32_e32 v30, 0xbfb8aa3b, v27
	ds_write_b32 v131, v30 offset:4148
	v_add_f32_e32 v27, v27, v24
	v_mul_f32_e32 v30, 0xbfb8aa3b, v27
	ds_write_b32 v131, v30 offset:4152
	v_add_f32_e32 v27, v27, v25
	v_mul_f32_e32 v30, 0xbfb8aa3b, v27
	ds_write_b32 v131, v30 offset:4156
	v_add_f32_e32 v27, v27, v26
	v_mul_f32_e32 v30, 0xbfb8aa3b, v27
	ds_write_b32 v131, v30 offset:4160
	s_mov_b64 exec, s[22:23]
